# v87 + cross-attention precompute GEMMs of layer 0 (96+96 units) run on the 64 workgroups that have no mLSTM scan item, concurrently with the scan instead of after it
# baseline (speedup 1.0000x reference)
.LBB0_231:
	s_add_u32 s28, s58, 0x4480000
	s_waitcnt vmcnt(0)
	v_mbcnt_lo_u32_b32 v0, -1, 0
	s_addc_u32 s29, s59, 0
	v_mbcnt_hi_u32_b32 v0, -1, v0
	v_readlane_b32 s0, v255, 7
	s_sub_i32 s98, s91, 0xc0
	s_cmpk_lt_i32 s91, 0xc0
	s_cselect_b32 s98, 0x4000, s98
	s_movk_i32 s99, 64
	s_cmpk_lt_i32 s98, 0x60
	s_nop 0
	v_add_u32_e32 v58, s0, v0
	v_mov_b32_e32 v8, v58
	s_cselect_b64 s[0:1], -1, 0
	s_and_b64 vcc, exec, s[0:1]
	v_readfirstlane_b32 s30, v8
	s_cbranch_vccz .LBB0_241
	v_lshlrev_b32_e32 v0, 4, v8
	v_add_u32_e32 v1, 0x2000, v0
	v_ashrrev_i32_e32 v2, 31, v1
	v_lshrrev_b32_e32 v2, 22, v2
	v_add_u32_e32 v2, v1, v2
	v_ashrrev_i32_e32 v2, 10, v2
	v_mul_i32_i24_e32 v3, 0x400, v2
	v_sub_u32_e32 v1, v1, v3
	v_lshrrev_b32_e32 v3, 4, v1
	v_bitop3_b32 v1, v3, v1, 32 bitop3:0x6c
	v_ashrrev_i32_e32 v3, 31, v1
	v_lshrrev_b32_e32 v3, 26, v3
	v_add_u32_e32 v3, v1, v3
	v_lshlrev_b32_e32 v5, 3, v2
	v_ashrrev_i32_e32 v4, 6, v3
	v_and_b32_e32 v5, -16, v5
	v_and_b32_e32 v3, 0xc0, v3
	v_add_u32_e32 v5, v4, v5
	v_sub_u32_e32 v1, v1, v3
	v_mov_b32_e32 v3, 1
	v_and_b32_e32 v4, 3, v4
	s_mov_b32 s3, 0x1fffe0
	v_lshrrev_b32_e32 v6, 2, v5
	v_lshlrev_b32_e32 v7, 1, v5
	v_lshlrev_b32_e32 v2, 5, v2
	v_ashrrev_i16_sdwa v1, v3, sext(v1) dst_sel:DWORD dst_unused:UNUSED_PAD src0_sel:DWORD src1_sel:BYTE_0
	v_and_or_b32 v4, v5, s3, v4
	v_and_b32_e32 v6, 4, v6
	v_and_b32_e32 v7, 24, v7
	v_and_b32_e32 v2, 32, v2
	v_bfe_i32 v1, v1, 0, 16
	v_or3_b32 v4, v4, v6, v7
	v_add_lshl_u32 v1, v2, v1, 1
	v_lshl_add_u32 v48, v4, 11, v1
	v_lshl_add_u32 v50, v5, 12, v1
	v_bfe_i32 v1, v8, 27, 1
	v_lshrrev_b32_e32 v1, 22, v1
	v_add_u32_e32 v1, v0, v1
	v_and_b32_e32 v1, 0xfffffc00, v1
	v_sub_u32_e32 v0, v0, v1
	v_lshrrev_b32_e32 v1, 4, v0
	v_ashrrev_i32_e32 v4, 31, v8
	v_bitop3_b32 v0, v1, v0, 32 bitop3:0x6c
	v_lshrrev_b32_e32 v4, 26, v4
	v_ashrrev_i32_e32 v1, 31, v0
	v_add_u32_e32 v4, v8, v4
	v_lshrrev_b32_e32 v1, 26, v1
	v_ashrrev_i32_e32 v4, 6, v4
	v_add_u32_e32 v1, v0, v1
	v_lshlrev_b32_e32 v5, 3, v4
	v_ashrrev_i32_e32 v2, 6, v1
	v_and_b32_e32 v5, -16, v5
	s_add_u32 s31, s58, 0x1180000
	v_add_u32_e32 v5, v2, v5
	v_and_b32_e32 v2, 3, v2
	s_addc_u32 s33, s59, 0
	v_and_or_b32 v2, v5, s3, v2
	s_ashr_i32 s3, s98, 31
	s_lshr_b32 s3, s3, 28
	s_add_i32 s3, s98, s3
	s_ashr_i32 s6, s3, 4
	s_lshl_b32 s5, s98, 6
	s_ashr_i32 s2, s30, 6
	s_ashr_i32 s7, s6, 31
	s_and_b32 s56, s5, 0x300
	s_ashr_i32 s4, s30, 8
	s_lshl_b32 s34, s2, 10
	s_and_b32 s3, s98, 3
	s_lshl_b64 s[22:23], s[6:7], 20
	s_lshl_b32 s5, s56, 1
	s_add_u32 s6, s28, s22
	s_addc_u32 s7, s29, s23
	v_and_b32_e32 v1, 0xc0, v1
	s_add_u32 s24, s6, s5
	v_sub_u32_e32 v0, v0, v1
	s_addc_u32 s25, s7, 0
	s_lshl_b32 s6, s3, 19
	v_lshrrev_b32_e32 v6, 2, v5
	v_lshlrev_b32_e32 v7, 1, v5
	v_lshlrev_b32_e32 v4, 5, v4
	v_ashrrev_i16_sdwa v0, v3, sext(v0) dst_sel:DWORD dst_unused:UNUSED_PAD src0_sel:DWORD src1_sel:BYTE_0
	s_or_b32 s5, s5, s6
	v_and_b32_e32 v6, 4, v6
	v_and_b32_e32 v7, 24, v7
	v_and_b32_e32 v4, 32, v4
	v_bfe_i32 v0, v0, 0, 16
	s_add_u32 s26, s31, s5
	v_or3_b32 v2, v2, v6, v7
	v_add_lshl_u32 v0, v4, v0, 1
	s_addc_u32 s27, s33, 0
	s_add_i32 s35, s34, 0
	v_lshl_add_u32 v52, v2, 11, v0
	s_add_i32 m0, s35, 0x10000
	v_lshl_add_u32 v54, v5, 12, v0
	global_load_lds_dwordx4 v52, s[26:27]
	s_add_i32 m0, s35, 0x12000
	s_add_i32 s36, s35, 0x2000
	global_load_lds_dwordx4 v48, s[26:27]
	s_mov_b32 m0, s35
	s_add_u32 s6, s26, 0x40000
	global_load_lds_dwordx4 v54, s[24:25]
	s_mov_b32 m0, s36
	s_addc_u32 s7, s27, 0
	global_load_lds_dwordx4 v50, s[24:25]
	s_add_i32 m0, s35, 0x14000
	v_mov_b32_e32 v53, 0
	global_load_lds_dwordx4 v52, s[6:7]
	s_add_i32 m0, s35, 0x16000
	v_mov_b32_e32 v49, v53
	global_load_lds_dwordx4 v48, s[6:7]
	s_add_u32 s6, s24, 0x80000
	s_addc_u32 s7, s25, 0
	s_add_i32 s37, s35, 0x4000
	s_mov_b32 m0, s37
	s_add_i32 s38, s35, 0x6000
	global_load_lds_dwordx4 v54, s[6:7]
	s_mov_b32 m0, s38
	v_mov_b32_e32 v55, v53
	global_load_lds_dwordx4 v50, s[6:7]
	v_mov_b32_e32 v51, v53
	v_lshl_add_u64 v[6:7], s[26:27], 0, v[52:53]
	v_lshl_add_u64 v[4:5], s[26:27], 0, v[48:49]
	v_lshl_add_u64 v[2:3], s[24:25], 0, v[54:55]
	s_cmp_lg_u32 s4, 1
	v_lshl_add_u64 v[0:1], s[24:25], 0, v[50:51]
	s_cbranch_scc1 .LBB0_234
	s_barrier
.LBB0_234:
	v_readlane_b32 s8, v254, 60
	v_readlane_b32 s10, v254, 62
	v_readlane_b32 s11, v254, 63
	s_add_u32 s39, s10, 0x4a80000
	s_addc_u32 s40, s11, 0
	s_lshl_b32 s2, s2, 5
	s_and_b32 s8, s2, 0x60
	s_lshl_b32 s57, s3, 8
	s_mov_b64 s[2:3], 0x80
	v_readlane_b32 s9, v254, 61
	s_add_i32 m0, s35, 0x18000
	v_lshl_add_u64 v[6:7], v[6:7], 0, s[2:3]
	s_lshl_b32 s5, s4, 13
	s_lshl_b32 s9, s8, 7
	s_waitcnt vmcnt(4)
	s_barrier
	global_load_lds_dwordx4 v[6:7], off
	v_lshl_add_u64 v[4:5], v[4:5], 0, s[2:3]
	s_add_i32 m0, s35, 0x1a000
	s_add_i32 s41, s35, 0x8000
	s_add_i32 s42, s35, 0xa000
	global_load_lds_dwordx4 v[4:5], off
	v_lshl_add_u64 v[2:3], v[2:3], 0, s[2:3]
	s_mov_b32 m0, s41
	s_add_u32 s6, s26, 0x40080
	global_load_lds_dwordx4 v[2:3], off
	v_lshl_add_u64 v[0:1], v[0:1], 0, s[2:3]
	s_mov_b32 m0, s42
	s_addc_u32 s7, s27, 0
	global_load_lds_dwordx4 v[0:1], off
	s_add_i32 m0, s35, 0x1c000
	v_lshl_add_u64 v[0:1], s[6:7], 0, v[52:53]
	global_load_lds_dwordx4 v[0:1], off
	v_lshl_add_u64 v[0:1], s[6:7], 0, v[48:49]
	s_add_i32 m0, s35, 0x1e000
	s_add_i32 s45, 0, 0x10000
	global_load_lds_dwordx4 v[0:1], off
	v_lshrrev_b32_e32 v1, 1, v8
	v_and_b32_e32 v1, 24, v1
	v_and_b32_e32 v0, 15, v8
	v_lshlrev_b32_e32 v2, 1, v1
	v_lshl_or_b32 v59, s4, 6, v0
	v_lshl_or_b32 v0, v0, 6, v2
	v_lshlrev_b32_e32 v2, 2, v8
	v_and_b32_e32 v2, 32, v2
	s_waitcnt vmcnt(6)
	v_bitop3_b32 v3, v0, s5, v2 bitop3:0xde
	v_bitop3_b32 v60, v0, s9, v2 bitop3:0xde
	s_add_i32 s4, s98, s99
	s_add_i32 s48, 0, 0x14000
	v_or_b32_e32 v61, s8, v1
	s_lshl_b32 s43, s4, 6
	s_lshl_b32 s44, s99, 6
	v_add_u32_e32 v62, s45, v60
	v_add_u32_e32 v63, 0, v3
	s_add_i32 s46, s35, 0xc000
	s_add_i32 s47, s35, 0xe000
	v_add_u32_e32 v64, s48, v60
	s_mov_b64 s[4:5], 0x100
	s_mov_b64 s[6:7], 0x180
	s_mov_b32 s49, 0x40000
	s_mov_b64 s[8:9], 0x48000
	s_mov_b32 s50, 0x48000
	s_mov_b64 s[10:11], 0x50000
	s_mov_b32 s51, 0x50000
	s_mov_b64 s[12:13], 0x58000
	s_mov_b32 s52, 0x58000
	s_mov_b32 s53, s98
	s_mov_b64 s[18:19], s[26:27]
	s_mov_b64 s[16:17], s[24:25]
	s_barrier
	s_branch .LBB0_236

.LBB0_236:
	s_add_i32 s53, s99, s53
	s_cmpk_gt_i32 s53, 0x5f
	s_cselect_b64 s[20:21], -1, 0
	s_and_b64 vcc, exec, s[20:21]
	s_cbranch_vccnz .LBB0_235
	s_ashr_i32 s14, s53, 31
	s_lshr_b32 s14, s14, 28
	s_add_i32 s14, s53, s14
	s_ashr_i32 s14, s14, 4
	s_ashr_i32 s15, s14, 31
	s_and_b32 s54, s43, 0x300
	s_and_b32 s55, s53, 3
	s_lshl_b64 s[14:15], s[14:15], 20
	s_lshl_b32 s18, s54, 1
	s_add_u32 s16, s28, s14
	s_addc_u32 s17, s29, s15
	s_add_u32 s16, s16, s18
	s_addc_u32 s17, s17, 0
	s_lshl_b32 s19, s55, 19
	s_or_b32 s18, s18, s19
	s_add_u32 s18, s31, s18
	s_addc_u32 s19, s33, 0
	s_lshl_b32 s55, s55, 8
	s_branch .LBB0_235

.LBB0_241:
	s_andn2_b64 vcc, exec, s[0:1]
	v_readfirstlane_b32 s30, v58
	s_cbranch_vccnz .LBB0_251
	v_lshlrev_b32_e32 v0, 4, v58
	v_add_u32_e32 v1, 0x2000, v0
	v_ashrrev_i32_e32 v2, 31, v1
	v_lshrrev_b32_e32 v2, 22, v2
	v_add_u32_e32 v2, v1, v2
	v_ashrrev_i32_e32 v2, 10, v2
	v_mul_i32_i24_e32 v3, 0x400, v2
	v_sub_u32_e32 v1, v1, v3
	v_lshrrev_b32_e32 v3, 4, v1
	v_bitop3_b32 v1, v3, v1, 32 bitop3:0x6c
	v_ashrrev_i32_e32 v3, 31, v1
	v_lshrrev_b32_e32 v3, 26, v3
	v_add_u32_e32 v3, v1, v3
	v_lshlrev_b32_e32 v5, 3, v2
	v_ashrrev_i32_e32 v4, 6, v3
	v_and_b32_e32 v5, -16, v5
	v_and_b32_e32 v3, 0xc0, v3
	v_add_u32_e32 v5, v4, v5
	v_sub_u32_e32 v1, v1, v3
	v_mov_b32_e32 v3, 1
	v_and_b32_e32 v4, 3, v4
	s_mov_b32 s1, 0xfffe0
	v_lshrrev_b32_e32 v6, 2, v5
	v_lshlrev_b32_e32 v7, 1, v5
	v_lshlrev_b32_e32 v2, 5, v2
	v_ashrrev_i16_sdwa v1, v3, sext(v1) dst_sel:DWORD dst_unused:UNUSED_PAD src0_sel:DWORD src1_sel:BYTE_0
	v_and_or_b32 v4, v5, s1, v4
	v_and_b32_e32 v6, 4, v6
	v_and_b32_e32 v7, 24, v7
	v_and_b32_e32 v2, 32, v2
	v_bfe_i32 v1, v1, 0, 16
	v_or3_b32 v4, v4, v6, v7
	v_add_lshl_u32 v1, v2, v1, 1
	v_lshl_add_u32 v44, v4, 12, v1
	v_lshl_add_u32 v46, v5, 11, v1
	v_bfe_i32 v1, v58, 27, 1
	v_lshrrev_b32_e32 v1, 22, v1
	v_add_u32_e32 v1, v0, v1
	v_and_b32_e32 v1, 0xfffffc00, v1
	v_sub_u32_e32 v0, v0, v1
	v_lshrrev_b32_e32 v1, 4, v0
	v_ashrrev_i32_e32 v4, 31, v58
	v_bitop3_b32 v0, v1, v0, 32 bitop3:0x6c
	v_lshrrev_b32_e32 v4, 26, v4
	v_ashrrev_i32_e32 v1, 31, v0
	v_add_u32_e32 v4, v58, v4
	v_lshrrev_b32_e32 v1, 26, v1
	v_ashrrev_i32_e32 v4, 6, v4
	v_add_u32_e32 v1, v0, v1
	v_lshlrev_b32_e32 v5, 3, v4
	v_ashrrev_i32_e32 v2, 6, v1
	v_and_b32_e32 v5, -16, v5
	s_add_u32 s31, s58, 0x1780000
	v_add_u32_e32 v5, v2, v5
	v_and_b32_e32 v2, 3, v2
	s_addc_u32 s33, s59, 0
	v_and_or_b32 v2, v5, s1, v2
	s_ashr_i32 s1, s98, 31
	s_lshr_b32 s1, s1, 28
	s_add_i32 s1, s98, s1
	s_lshl_b32 s3, s98, 6
	s_ashr_i32 s2, s1, 4
	s_and_b32 s1, s98, 3
	s_and_b32 s53, s3, 0x300
	s_ashr_i32 s0, s30, 6
	s_lshl_b32 s3, s1, 19
	s_lshl_b32 s5, s53, 1
	s_ashr_i32 s4, s30, 8
	s_lshl_b32 s34, s0, 10
	s_or_b32 s3, s5, s3
	s_add_u32 s24, s31, s3
	v_and_b32_e32 v1, 0xc0, v1
	s_addc_u32 s25, s33, 0
	s_ashr_i32 s3, s2, 31
	v_sub_u32_e32 v0, v0, v1
	s_lshl_b64 s[22:23], s[2:3], 20
	v_lshrrev_b32_e32 v6, 2, v5
	v_lshlrev_b32_e32 v7, 1, v5
	v_lshlrev_b32_e32 v4, 5, v4
	v_ashrrev_i16_sdwa v0, v3, sext(v0) dst_sel:DWORD dst_unused:UNUSED_PAD src0_sel:DWORD src1_sel:BYTE_0
	s_add_u32 s2, s28, s22
	v_and_b32_e32 v6, 4, v6
	v_and_b32_e32 v7, 24, v7
	v_and_b32_e32 v4, 32, v4
	v_bfe_i32 v0, v0, 0, 16
	s_addc_u32 s3, s29, s23
	v_or3_b32 v2, v2, v6, v7
	v_add_lshl_u32 v0, v4, v0, 1
	s_add_u32 s2, s2, s5
	v_lshl_add_u32 v48, v2, 12, v0
	s_addc_u32 s3, s3, 0
	v_mov_b32_e32 v49, 0
	v_lshl_add_u32 v50, v5, 11, v0
	s_add_i32 s35, s34, 0
	v_lshl_add_u64 v[0:1], s[2:3], 0, v[48:49]
	s_mov_b64 s[6:7], 0x800
	s_add_i32 m0, s35, 0x10000
	v_lshl_add_u64 v[2:3], v[0:1], 0, s[6:7]
	v_mov_b32_e32 v45, v49
	global_load_lds_dwordx4 v[2:3], off
	v_lshl_add_u64 v[2:3], s[2:3], 0, v[44:45]
	v_lshl_add_u64 v[4:5], v[2:3], 0, s[6:7]
	s_add_i32 m0, s35, 0x12000
	s_add_i32 s36, s35, 0x2000
	global_load_lds_dwordx4 v[4:5], off
	s_mov_b32 m0, s35
	s_add_u32 s6, s2, 0x80800
	global_load_lds_dwordx4 v50, s[24:25]
	s_mov_b32 m0, s36
	s_addc_u32 s7, s3, 0
	global_load_lds_dwordx4 v46, s[24:25]
	s_add_i32 m0, s35, 0x14000
	v_mov_b32_e32 v51, v49
	global_load_lds_dwordx4 v48, s[6:7]
	s_add_i32 m0, s35, 0x16000
	v_mov_b32_e32 v47, v49
	global_load_lds_dwordx4 v44, s[6:7]
	s_add_u32 s6, s24, 0x40000
	s_addc_u32 s7, s25, 0
	s_add_i32 s37, s35, 0x4000
	s_mov_b32 m0, s37
	s_add_i32 s38, s35, 0x6000
	global_load_lds_dwordx4 v50, s[6:7]
	s_mov_b32 m0, s38
	v_lshl_add_u64 v[6:7], s[24:25], 0, v[50:51]
	global_load_lds_dwordx4 v46, s[6:7]
	s_cmp_lg_u32 s4, 1
	v_lshl_add_u64 v[4:5], s[24:25], 0, v[46:47]
	s_cbranch_scc1 .LBB0_244
	s_barrier
.LBB0_244:
	s_add_u32 s26, s2, 0x800
	s_addc_u32 s27, s3, 0
	s_lshl_b32 s54, s1, 8
	s_add_u32 s39, s58, 0x5680000
	s_addc_u32 s40, s59, 0
	s_lshl_b32 s0, s0, 5
	s_and_b32 s6, s0, 0x60
	s_mov_b64 s[0:1], 0x880
	s_add_i32 m0, s35, 0x18000
	v_lshl_add_u64 v[0:1], v[0:1], 0, s[0:1]
	s_lshl_b32 s5, s4, 13
	s_lshl_b32 s7, s6, 7
	s_waitcnt vmcnt(4)
	s_barrier
	global_load_lds_dwordx4 v[0:1], off
	v_lshl_add_u64 v[0:1], v[2:3], 0, s[0:1]
	s_add_i32 m0, s35, 0x1a000
	s_mov_b64 s[0:1], 0x80
	s_add_i32 s41, s35, 0x8000
	s_add_i32 s42, s35, 0xa000
	global_load_lds_dwordx4 v[0:1], off
	v_lshl_add_u64 v[0:1], v[6:7], 0, s[0:1]
	s_mov_b32 m0, s41
	s_add_u32 s2, s2, 0x80880
	global_load_lds_dwordx4 v[0:1], off
	v_lshl_add_u64 v[0:1], v[4:5], 0, s[0:1]
	s_mov_b32 m0, s42
	s_addc_u32 s3, s3, 0
	global_load_lds_dwordx4 v[0:1], off
	s_add_i32 m0, s35, 0x1c000
	v_lshl_add_u64 v[0:1], s[2:3], 0, v[48:49]
	global_load_lds_dwordx4 v[0:1], off
	v_lshl_add_u64 v[0:1], s[2:3], 0, v[44:45]
	s_add_i32 m0, s35, 0x1e000
	s_add_i32 s2, s98, s99
	global_load_lds_dwordx4 v[0:1], off
	v_lshrrev_b32_e32 v1, 1, v58
	v_and_b32_e32 v1, 24, v1
	v_and_b32_e32 v0, 15, v58
	v_lshlrev_b32_e32 v2, 1, v1
	v_lshl_or_b32 v54, s4, 6, v0
	v_lshl_or_b32 v0, v0, 6, v2
	v_lshlrev_b32_e32 v2, 2, v58
	v_and_b32_e32 v2, 32, v2
	s_waitcnt vmcnt(6)
	v_bitop3_b32 v3, v0, s5, v2 bitop3:0xde
	v_bitop3_b32 v55, v0, s7, v2 bitop3:0xde
	s_add_i32 s45, 0, 0x14000
	v_or_b32_e32 v56, s6, v1
	s_lshl_b32 s43, s2, 6
	s_lshl_b32 s44, s99, 6
	v_add_u32_e32 v57, 0, v3
	v_add_u32_e32 v58, s45, v55
	s_mov_b64 s[2:3], 0x100
	s_mov_b64 s[4:5], 0x180
	s_mov_b64 s[6:7], 0x18000
	s_mov_b32 s46, 0x40000
	s_mov_b64 s[8:9], 0x48000
	s_mov_b32 s47, 0x48000
	s_mov_b64 s[10:11], 0x50000
	s_mov_b32 s48, 0x50000
	s_mov_b64 s[12:13], 0x58000
	s_mov_b32 s49, 0x58000
	s_mov_b32 s50, s98
	s_mov_b64 s[18:19], s[26:27]
	s_mov_b64 s[14:15], s[24:25]
	s_barrier
	s_branch .LBB0_246

.LBB0_246:
	s_add_i32 s50, s99, s50
	s_cmpk_gt_i32 s50, 0x5f
	s_cselect_b64 s[20:21], -1, 0
	s_and_b64 vcc, exec, s[20:21]
	s_cbranch_vccnz .LBB0_245
	s_ashr_i32 s14, s50, 31
	s_lshr_b32 s14, s14, 28
	s_add_i32 s14, s50, s14
	s_and_b32 s52, s50, 3
	s_and_b32 s51, s43, 0x300
	s_ashr_i32 s16, s14, 4
	s_lshl_b32 s14, s52, 19
	s_lshl_b32 s18, s51, 1
	s_or_b32 s14, s18, s14
	s_add_u32 s14, s31, s14
	s_addc_u32 s15, s33, 0
	s_ashr_i32 s17, s16, 31
	s_lshl_b64 s[16:17], s[16:17], 20
	s_add_u32 s19, s28, s16
	s_addc_u32 s55, s29, s17
	s_add_u32 s18, s19, s18
	s_addc_u32 s19, s55, 0
	s_add_u32 s18, s18, 0x800
	s_addc_u32 s19, s19, 0
	s_lshl_b32 s52, s52, 8
	s_branch .LBB0_245
